# v024 + scan1 inner loop unrolled by four: 64 loads issued before the first 8-step group is consumed (8 serialized round trips per chunk instead of 32)
# speedup vs baseline: 1.0026x; 1.0026x over previous
; DI float bf1(const bf16_t* p) { return __uint_as_float((unsigned)(*(GAS const bf16_t*)p) << 16); }
; DI int obid() { int b = blockIdx.x; asm volatile("" : "+s"(b)); return b; }
; DI void phase_scan1(const bf16_t* A, const bf16_t* U, float* agg) {
;     ...
;     for (int it = obid(); it < 256; it += gridDim.x) {
;         const int b = it >> 4, c = it & 15; const size_t base = ((size_t)b * TT + (size_t)c * 257) * 512 + ch;
;         float Pl = 0.f, S = 0.f;
;         for (int s0 = 0; s0 < 256; s0 += 8) {
;             float a[8], u[8];
; #pragma unroll
;             for (int e = 0; e < 8; ++e) { a[e] = bf1(A + base + (size_t)(s0 + e) * 512); u[e] = bf1(U + base + (size_t)(s0 + e) * 512); }
.LBB0_132:
	v_add_co_u32_e32 v8, vcc, 0xf7f7f000, v6
	global_load_ushort v14, v[6:7], off offset:-4096
	global_load_ushort v15, v[6:7], off offset:-3072
	global_load_ushort v16, v[6:7], off offset:-2048
	global_load_ushort v17, v[6:7], off offset:-1024
	global_load_ushort v18, v[6:7], off
	v_addc_co_u32_e32 v9, vcc, -1, v7, vcc
	v_add_co_u32_e32 v10, vcc, 0xfffff000, v6
	s_add_i32 s7, s7, 8
	s_nop 0
	v_addc_co_u32_e32 v11, vcc, -1, v7, vcc
	v_add_co_u32_e32 v12, vcc, 0xf7f80000, v6
	s_waitcnt lgkmcnt(0)
	global_load_ushort v19, v[8:9], off offset:-3072
	global_load_ushort v20, v[8:9], off offset:-1024
	global_load_ushort v21, v[10:11], off offset:-3072
	global_load_ushort v22, v[10:11], off offset:-2048
	s_nop 0
	global_load_ushort v11, v[10:11], off offset:-1024
	v_addc_co_u32_e32 v13, vcc, -1, v7, vcc
	global_load_ushort v23, v[12:13], off offset:-3072
	global_load_ushort v24, v[12:13], off offset:-1024
	global_load_ushort v25, v[8:9], off
	s_nop 0
	global_load_ushort v9, v[8:9], off offset:-2048
	s_nop 0
	global_load_ushort v26, v[12:13], off
	s_nop 0
	global_load_ushort v13, v[12:13], off offset:-2048
	s_cmpk_lt_u32 s7, 0xf8
	v_lshl_add_u64 v[6:7], v[6:7], 0, s[74:75]
	v_add_co_u32_e32 v40, vcc, 0xf7f7f000, v6
	global_load_ushort v46, v[6:7], off offset:-4096
	global_load_ushort v47, v[6:7], off offset:-3072
	global_load_ushort v48, v[6:7], off offset:-2048
	global_load_ushort v49, v[6:7], off offset:-1024
	global_load_ushort v50, v[6:7], off
	v_addc_co_u32_e32 v41, vcc, -1, v7, vcc
	v_add_co_u32_e32 v42, vcc, 0xfffff000, v6
	s_add_i32 s7, s7, 8
	s_nop 0
	v_addc_co_u32_e32 v43, vcc, -1, v7, vcc
	v_add_co_u32_e32 v44, vcc, 0xf7f80000, v6
	s_waitcnt lgkmcnt(0)
	global_load_ushort v51, v[40:41], off offset:-3072
	global_load_ushort v52, v[40:41], off offset:-1024
	global_load_ushort v53, v[42:43], off offset:-3072
	global_load_ushort v54, v[42:43], off offset:-2048
	s_nop 0
	global_load_ushort v43, v[42:43], off offset:-1024
	v_addc_co_u32_e32 v45, vcc, -1, v7, vcc
	global_load_ushort v55, v[44:45], off offset:-3072
	global_load_ushort v56, v[44:45], off offset:-1024
	global_load_ushort v57, v[40:41], off
	s_nop 0
	global_load_ushort v41, v[40:41], off offset:-2048
	s_nop 0
	global_load_ushort v58, v[44:45], off
	s_nop 0
	global_load_ushort v45, v[44:45], off offset:-2048
	s_cmpk_lt_u32 s7, 0xf8
	v_lshl_add_u64 v[6:7], v[6:7], 0, s[74:75]
	v_add_co_u32_e32 v72, vcc, 0xf7f7f000, v6
	global_load_ushort v78, v[6:7], off offset:-4096
	global_load_ushort v79, v[6:7], off offset:-3072
	global_load_ushort v80, v[6:7], off offset:-2048
	global_load_ushort v81, v[6:7], off offset:-1024
	global_load_ushort v82, v[6:7], off
	v_addc_co_u32_e32 v73, vcc, -1, v7, vcc
	v_add_co_u32_e32 v74, vcc, 0xfffff000, v6
	s_add_i32 s7, s7, 8
	s_nop 0
	v_addc_co_u32_e32 v75, vcc, -1, v7, vcc
	v_add_co_u32_e32 v76, vcc, 0xf7f80000, v6
	s_waitcnt lgkmcnt(0)
	global_load_ushort v83, v[72:73], off offset:-3072
	global_load_ushort v84, v[72:73], off offset:-1024
	global_load_ushort v85, v[74:75], off offset:-3072
	global_load_ushort v86, v[74:75], off offset:-2048
	s_nop 0
	global_load_ushort v75, v[74:75], off offset:-1024
	v_addc_co_u32_e32 v77, vcc, -1, v7, vcc
	global_load_ushort v87, v[76:77], off offset:-3072
	global_load_ushort v88, v[76:77], off offset:-1024
	global_load_ushort v89, v[72:73], off
	s_nop 0
	global_load_ushort v73, v[72:73], off offset:-2048
	s_nop 0
	global_load_ushort v90, v[76:77], off
	s_nop 0
	global_load_ushort v77, v[76:77], off offset:-2048
	s_cmpk_lt_u32 s7, 0xf8
	v_lshl_add_u64 v[6:7], v[6:7], 0, s[74:75]
	v_add_co_u32_e32 v104, vcc, 0xf7f7f000, v6
	global_load_ushort v110, v[6:7], off offset:-4096
	global_load_ushort v111, v[6:7], off offset:-3072
	global_load_ushort v112, v[6:7], off offset:-2048
	global_load_ushort v113, v[6:7], off offset:-1024
	global_load_ushort v114, v[6:7], off
	v_addc_co_u32_e32 v105, vcc, -1, v7, vcc
	v_add_co_u32_e32 v106, vcc, 0xfffff000, v6
	s_add_i32 s7, s7, 8
	s_nop 0
	v_addc_co_u32_e32 v107, vcc, -1, v7, vcc
	v_add_co_u32_e32 v108, vcc, 0xf7f80000, v6
	s_waitcnt lgkmcnt(0)
	global_load_ushort v115, v[104:105], off offset:-3072
	global_load_ushort v116, v[104:105], off offset:-1024
	global_load_ushort v117, v[106:107], off offset:-3072
	global_load_ushort v118, v[106:107], off offset:-2048
	s_nop 0
	global_load_ushort v107, v[106:107], off offset:-1024
	v_addc_co_u32_e32 v109, vcc, -1, v7, vcc
	global_load_ushort v119, v[108:109], off offset:-3072
	global_load_ushort v120, v[108:109], off offset:-1024
	global_load_ushort v121, v[104:105], off
	s_nop 0
	global_load_ushort v105, v[104:105], off offset:-2048
	s_nop 0
	global_load_ushort v122, v[108:109], off
	s_nop 0
	global_load_ushort v109, v[108:109], off offset:-2048
	s_cmpk_lt_u32 s7, 0xf8
	v_lshl_add_u64 v[6:7], v[6:7], 0, s[74:75]
	s_waitcnt vmcnt(48)
; DI float bf1(const bf16_t* p) { return __uint_as_float((unsigned)(*(GAS const bf16_t*)p) << 16); }
; DI void phase_scan1(const bf16_t* A, const bf16_t* U, float* agg) {
;     ...
;         for (int s0 = 0; s0 < 256; s0 += 8) {
;             float a[8], u[8];
; #pragma unroll
;             for (int e = 0; e < 8; ++e) { a[e] = bf1(A + base + (size_t)(s0 + e) * 512); u[e] = bf1(U + base + (size_t)(s0 + e) * 512); }
; #pragma unroll
;             for (int e = 0; e < 8; ++e) { S = __expf(a[e]) * S + u[e]; Pl += a[e]; }
;         }
	v_lshlrev_b32_e32 v27, 16, v14
	v_lshlrev_b32_e32 v8, 16, v15
	v_lshlrev_b32_e32 v10, 16, v16
	v_lshlrev_b32_e32 v12, 16, v17
	v_lshlrev_b32_e32 v14, 16, v18
	v_lshlrev_b32_e32 v15, 16, v19
	v_lshlrev_b32_e32 v17, 16, v20
	v_lshlrev_b32_e32 v19, 16, v23
	v_add_f32_e32 v5, v5, v15
	v_lshlrev_b32_e32 v29, 16, v11
	v_mul_f32_e32 v11, 0x3fb8aa3b, v15
	v_lshlrev_b32_e32 v9, 16, v9
	v_exp_f32_e32 v23, v11
	v_mul_f32_e32 v20, 0x3fb8aa3b, v9
	v_mul_f32_e32 v15, 0x3fb8aa3b, v17
	v_lshlrev_b32_e32 v11, 16, v25
	v_exp_f32_e32 v32, v20
	v_lshlrev_b32_e32 v28, 16, v21
	v_lshlrev_b32_e32 v21, 16, v24
	v_exp_f32_e32 v24, v15
	v_mul_f32_e32 v25, 0x3fb8aa3b, v11
	v_mul_f32_e32 v16, 0x3fb8aa3b, v19
	v_exp_f32_e32 v25, v25
	v_lshlrev_b32_e32 v22, 16, v22
	v_lshlrev_b32_e32 v13, 16, v13
	v_exp_f32_e32 v31, v16
	v_fmac_f32_e32 v28, v4, v23
	v_lshlrev_b32_e32 v15, 16, v26
	v_mul_f32_e32 v26, 0x3fb8aa3b, v13
	v_fmac_f32_e32 v22, v28, v32
	v_exp_f32_e32 v16, v26
	v_fmac_f32_e32 v29, v22, v24
	v_fmac_f32_e32 v27, v29, v25
	v_mul_f32_e32 v18, 0x3fb8aa3b, v21
	v_mul_f32_e32 v4, v27, v31
	v_exp_f32_e32 v18, v18
	v_pk_add_f32 v[4:5], v[4:5], v[8:9]
	v_mul_f32_e32 v30, 0x3fb8aa3b, v15
	v_pk_mul_f32 v[8:9], v[4:5], v[16:17]
	v_pk_add_f32 v[4:5], v[4:5], v[16:17]
	v_exp_f32_e32 v20, v30
	v_mov_b32_e32 v9, v5
	v_pk_add_f32 v[4:5], v[8:9], v[10:11]
	s_nop 0
	v_pk_mul_f32 v[8:9], v[4:5], v[18:19]
	v_pk_add_f32 v[4:5], v[4:5], v[18:19]
	s_nop 0
	v_mov_b32_e32 v9, v5
	v_pk_add_f32 v[4:5], v[8:9], v[12:13]
	s_nop 0
	v_pk_mul_f32 v[8:9], v[4:5], v[20:21]
	v_pk_add_f32 v[4:5], v[4:5], v[20:21]
	s_nop 0
	v_mov_b32_e32 v9, v5
	v_pk_add_f32 v[4:5], v[8:9], v[14:15]
	s_waitcnt vmcnt(32)
	v_lshlrev_b32_e32 v27, 16, v46
	v_lshlrev_b32_e32 v8, 16, v47
	v_lshlrev_b32_e32 v10, 16, v48
	v_lshlrev_b32_e32 v12, 16, v49
	v_lshlrev_b32_e32 v14, 16, v50
	v_lshlrev_b32_e32 v15, 16, v51
	v_lshlrev_b32_e32 v17, 16, v52
	v_lshlrev_b32_e32 v19, 16, v55
	v_add_f32_e32 v5, v5, v15
	v_lshlrev_b32_e32 v29, 16, v43
	v_mul_f32_e32 v11, 0x3fb8aa3b, v15
	v_lshlrev_b32_e32 v9, 16, v41
	v_exp_f32_e32 v23, v11
	v_mul_f32_e32 v20, 0x3fb8aa3b, v9
	v_mul_f32_e32 v15, 0x3fb8aa3b, v17
	v_lshlrev_b32_e32 v11, 16, v57
	v_exp_f32_e32 v32, v20
	v_lshlrev_b32_e32 v28, 16, v53
	v_lshlrev_b32_e32 v21, 16, v56
	v_exp_f32_e32 v24, v15
	v_mul_f32_e32 v25, 0x3fb8aa3b, v11
	v_mul_f32_e32 v16, 0x3fb8aa3b, v19
	v_exp_f32_e32 v25, v25
	v_lshlrev_b32_e32 v22, 16, v54
	v_lshlrev_b32_e32 v13, 16, v45
	v_exp_f32_e32 v31, v16
	v_fmac_f32_e32 v28, v4, v23
	v_lshlrev_b32_e32 v15, 16, v58
	v_mul_f32_e32 v26, 0x3fb8aa3b, v13
	v_fmac_f32_e32 v22, v28, v32
	v_exp_f32_e32 v16, v26
	v_fmac_f32_e32 v29, v22, v24
	v_fmac_f32_e32 v27, v29, v25
	v_mul_f32_e32 v18, 0x3fb8aa3b, v21
	v_mul_f32_e32 v4, v27, v31
	v_exp_f32_e32 v18, v18
	v_pk_add_f32 v[4:5], v[4:5], v[8:9]
	v_mul_f32_e32 v30, 0x3fb8aa3b, v15
	v_pk_mul_f32 v[8:9], v[4:5], v[16:17]
	v_pk_add_f32 v[4:5], v[4:5], v[16:17]
	v_exp_f32_e32 v20, v30
	v_mov_b32_e32 v9, v5
	v_pk_add_f32 v[4:5], v[8:9], v[10:11]
	s_nop 0
	v_pk_mul_f32 v[8:9], v[4:5], v[18:19]
	v_pk_add_f32 v[4:5], v[4:5], v[18:19]
	s_nop 0
	v_mov_b32_e32 v9, v5
	v_pk_add_f32 v[4:5], v[8:9], v[12:13]
	s_nop 0
	v_pk_mul_f32 v[8:9], v[4:5], v[20:21]
	v_pk_add_f32 v[4:5], v[4:5], v[20:21]
	s_nop 0
	v_mov_b32_e32 v9, v5
	v_pk_add_f32 v[4:5], v[8:9], v[14:15]
	s_waitcnt vmcnt(16)
	v_lshlrev_b32_e32 v27, 16, v78
	v_lshlrev_b32_e32 v8, 16, v79
	v_lshlrev_b32_e32 v10, 16, v80
	v_lshlrev_b32_e32 v12, 16, v81
	v_lshlrev_b32_e32 v14, 16, v82
	v_lshlrev_b32_e32 v15, 16, v83
	v_lshlrev_b32_e32 v17, 16, v84
	v_lshlrev_b32_e32 v19, 16, v87
	v_add_f32_e32 v5, v5, v15
	v_lshlrev_b32_e32 v29, 16, v75
	v_mul_f32_e32 v11, 0x3fb8aa3b, v15
	v_lshlrev_b32_e32 v9, 16, v73
	v_exp_f32_e32 v23, v11
	v_mul_f32_e32 v20, 0x3fb8aa3b, v9
	v_mul_f32_e32 v15, 0x3fb8aa3b, v17
	v_lshlrev_b32_e32 v11, 16, v89
	v_exp_f32_e32 v32, v20
	v_lshlrev_b32_e32 v28, 16, v85
	v_lshlrev_b32_e32 v21, 16, v88
	v_exp_f32_e32 v24, v15
	v_mul_f32_e32 v25, 0x3fb8aa3b, v11
	v_mul_f32_e32 v16, 0x3fb8aa3b, v19
	v_exp_f32_e32 v25, v25
	v_lshlrev_b32_e32 v22, 16, v86
	v_lshlrev_b32_e32 v13, 16, v77
	v_exp_f32_e32 v31, v16
	v_fmac_f32_e32 v28, v4, v23
	v_lshlrev_b32_e32 v15, 16, v90
	v_mul_f32_e32 v26, 0x3fb8aa3b, v13
	v_fmac_f32_e32 v22, v28, v32
	v_exp_f32_e32 v16, v26
	v_fmac_f32_e32 v29, v22, v24
	v_fmac_f32_e32 v27, v29, v25
	v_mul_f32_e32 v18, 0x3fb8aa3b, v21
	v_mul_f32_e32 v4, v27, v31
	v_exp_f32_e32 v18, v18
	v_pk_add_f32 v[4:5], v[4:5], v[8:9]
	v_mul_f32_e32 v30, 0x3fb8aa3b, v15
	v_pk_mul_f32 v[8:9], v[4:5], v[16:17]
	v_pk_add_f32 v[4:5], v[4:5], v[16:17]
	v_exp_f32_e32 v20, v30
	v_mov_b32_e32 v9, v5
	v_pk_add_f32 v[4:5], v[8:9], v[10:11]
	s_nop 0
	v_pk_mul_f32 v[8:9], v[4:5], v[18:19]
	v_pk_add_f32 v[4:5], v[4:5], v[18:19]
	s_nop 0
	v_mov_b32_e32 v9, v5
	v_pk_add_f32 v[4:5], v[8:9], v[12:13]
	s_nop 0
	v_pk_mul_f32 v[8:9], v[4:5], v[20:21]
	v_pk_add_f32 v[4:5], v[4:5], v[20:21]
	s_nop 0
	v_mov_b32_e32 v9, v5
	v_pk_add_f32 v[4:5], v[8:9], v[14:15]
	s_waitcnt vmcnt(0)
	v_lshlrev_b32_e32 v27, 16, v110
	v_lshlrev_b32_e32 v8, 16, v111
	v_lshlrev_b32_e32 v10, 16, v112
	v_lshlrev_b32_e32 v12, 16, v113
	v_lshlrev_b32_e32 v14, 16, v114
	v_lshlrev_b32_e32 v15, 16, v115
	v_lshlrev_b32_e32 v17, 16, v116
	v_lshlrev_b32_e32 v19, 16, v119
	v_add_f32_e32 v5, v5, v15
	v_lshlrev_b32_e32 v29, 16, v107
	v_mul_f32_e32 v11, 0x3fb8aa3b, v15
	v_lshlrev_b32_e32 v9, 16, v105
	v_exp_f32_e32 v23, v11
	v_mul_f32_e32 v20, 0x3fb8aa3b, v9
	v_mul_f32_e32 v15, 0x3fb8aa3b, v17
	v_lshlrev_b32_e32 v11, 16, v121
	v_exp_f32_e32 v32, v20
	v_lshlrev_b32_e32 v28, 16, v117
	v_lshlrev_b32_e32 v21, 16, v120
	v_exp_f32_e32 v24, v15
	v_mul_f32_e32 v25, 0x3fb8aa3b, v11
	v_mul_f32_e32 v16, 0x3fb8aa3b, v19
	v_exp_f32_e32 v25, v25
	v_lshlrev_b32_e32 v22, 16, v118
	v_lshlrev_b32_e32 v13, 16, v109
	v_exp_f32_e32 v31, v16
	v_fmac_f32_e32 v28, v4, v23
	v_lshlrev_b32_e32 v15, 16, v122
	v_mul_f32_e32 v26, 0x3fb8aa3b, v13
	v_fmac_f32_e32 v22, v28, v32
	v_exp_f32_e32 v16, v26
	v_fmac_f32_e32 v29, v22, v24
	v_fmac_f32_e32 v27, v29, v25
	v_mul_f32_e32 v18, 0x3fb8aa3b, v21
	v_mul_f32_e32 v4, v27, v31
	v_exp_f32_e32 v18, v18
	v_pk_add_f32 v[4:5], v[4:5], v[8:9]
	v_mul_f32_e32 v30, 0x3fb8aa3b, v15
	v_pk_mul_f32 v[8:9], v[4:5], v[16:17]
	v_pk_add_f32 v[4:5], v[4:5], v[16:17]
	v_exp_f32_e32 v20, v30
	v_mov_b32_e32 v9, v5
	v_pk_add_f32 v[4:5], v[8:9], v[10:11]
	s_nop 0
	v_pk_mul_f32 v[8:9], v[4:5], v[18:19]
	v_pk_add_f32 v[4:5], v[4:5], v[18:19]
	s_nop 0
	v_mov_b32_e32 v9, v5
	v_pk_add_f32 v[4:5], v[8:9], v[12:13]
	s_nop 0
	v_pk_mul_f32 v[8:9], v[4:5], v[20:21]
	v_pk_add_f32 v[4:5], v[4:5], v[20:21]
	s_nop 0
	v_mov_b32_e32 v9, v5
	v_pk_add_f32 v[4:5], v[8:9], v[14:15]
	s_cbranch_scc1 .LBB0_132
; DI float bf1(const bf16_t* p) { return __uint_as_float((unsigned)(*(GAS const bf16_t*)p) << 16); }
; DI int obid() { int b = blockIdx.x; asm volatile("" : "+s"(b)); return b; }
; DI void phase_scan1(const bf16_t* A, const bf16_t* U, float* agg) {
;     ...
;     for (int it = obid(); it < 256; it += gridDim.x) {
;         const int b = it >> 4, c = it & 15; const size_t base = ((size_t)b * TT + (size_t)c * 257) * 512 + ch;
;         float Pl = 0.f, S = 0.f;
;         for (int s0 = 0; s0 < 256; s0 += 8) {
;             float a[8], u[8];
; #pragma unroll
;             for (int e = 0; e < 8; ++e) { a[e] = bf1(A + base + (size_t)(s0 + e) * 512); u[e] = bf1(U + base + (size_t)(s0 + e) * 512); }
; #pragma unroll
;             for (int e = 0; e < 8; ++e) { S = __expf(a[e]) * S + u[e]; Pl += a[e]; }
;         }
;         { const float a = bf1(A + base + (size_t)256 * 512), u = bf1(U + base + (size_t)256 * 512); S = __expf(a) * S + u; Pl += a; }
;         agg[((size_t)it * 512 + ch) * 2] = __expf(Pl); agg[((size_t)it * 512 + ch) * 2 + 1] = S;
	s_and_b32 s7, s4, 15
	s_mul_hi_i32 s9, s5, 0x1010
	s_mulk_i32 s5, 0x1010
	s_mulk_i32 s7, 0x101
	s_add_u32 s8, s5, s7
	s_addc_u32 s9, s9, 0
	s_lshl_b64 s[8:9], s[8:9], 9
	v_lshl_add_u64 v[6:7], s[8:9], 0, v[0:1]
	v_lshlrev_b64 v[6:7], 1, v[6:7]
	v_lshl_add_u64 v[8:9], s[28:29], 0, v[6:7]
	s_mov_b32 s5, 0x40000
	v_add_co_u32_e32 v8, vcc, s5, v8
	v_lshl_add_u64 v[6:7], s[38:39], 0, v[6:7]
	s_nop 0
	v_addc_co_u32_e32 v9, vcc, 0, v9, vcc
	global_load_ushort v8, v[8:9], off
	v_add_co_u32_e32 v6, vcc, s5, v6
	s_ashr_i32 s5, s4, 31
	s_nop 0
	v_addc_co_u32_e32 v7, vcc, 0, v7, vcc
	global_load_ushort v9, v[6:7], off
	s_add_i32 s6, s6, s62
	s_lshl_b64 s[8:9], s[4:5], 12
	s_add_i32 s4, s4, s62
	v_lshl_add_u64 v[6:7], v[2:3], 0, s[8:9]
	s_cmpk_gt_i32 s4, 0xff
	s_waitcnt vmcnt(1)
	v_lshlrev_b32_e32 v8, 16, v8
	v_mul_f32_e32 v10, 0x3fb8aa3b, v8
	v_add_f32_e32 v5, v5, v8
	v_exp_f32_e32 v10, v10
	v_mul_f32_e32 v5, 0x3fb8aa3b, v5
	v_exp_f32_e32 v8, v5
	s_waitcnt vmcnt(0)
	v_lshlrev_b32_e32 v9, 16, v9
	v_fmac_f32_e32 v9, v4, v10
	flat_store_dwordx2 v[6:7], v[8:9]
	s_cbranch_scc0 .LBB0_131
